# barrier: first arriver of an XCD starts L2 write-back early at full seams; early L1 invalidate at XCD-local seams
# speedup vs baseline: 1.0086x; 1.0086x over previous
; __device__ __forceinline__ unsigned xb_ld(unsigned* p)              { return __hip_atomic_load(p, __ATOMIC_RELAXED, __HIP_MEMORY_SCOPE_AGENT); }
; __device__ __forceinline__ unsigned xb_add(unsigned* p, unsigned v) { return __hip_atomic_fetch_add(p, v, __ATOMIC_RELAXED, __HIP_MEMORY_SCOPE_AGENT); }
; #define XB_SPIN(cond, bar) do { unsigned _sp = 0; while (cond) { __builtin_amdgcn_s_sleep(1); \
;     if ((++_sp & 255u) == 0u) { if (xb_ld(&(bar)[XB_TMO])) break; if (_sp > XB_SPIN_CAP) { atomicAdd(&(bar)[XB_TMO], 1u); break; } } } } while (0)
; __device__ __forceinline__ void xcd_barrier(const XcdBarrier& b) {
;     ...
;         const unsigned old = xb_add(&bar[XB_XSUB(b.x)], 1u);
;         const unsigned gen = old / nloc;
;         if (old + 1u == (gen + 1u) * nloc) {
;             __builtin_amdgcn_fence(__ATOMIC_RELEASE, "agent");
;             asm volatile("s_waitcnt vmcnt(0)" ::: "memory");
;             const unsigned og = xb_add(&bar[XB_TOP], 1u);
;             const unsigned tg = og / nx;
;             if (og + 1u == (tg + 1u) * nx) xb_add(&bar[XB_TOPGEN], 1u);
;             else XB_SPIN(xb_ld(&bar[XB_TOPGEN]) == tg, bar);
;             __builtin_amdgcn_fence(__ATOMIC_ACQUIRE, "agent");
;             xb_add(&bar[XB_XGEN(b.x)], 1u);
;             asm volatile("s_waitcnt vmcnt(0)" ::: "memory");
;         } else {
;             XB_SPIN(xb_ld(&bar[XB_XGEN(b.x)]) == gen, bar);
.LBB0_800:
	v_readlane_b32 s8, v254, 52
	s_add_u32 s8, s2, s8
	s_addc_u32 s9, s3, 0
	v_cvt_f32_u32_e32 v0, v3
	v_sub_u32_e32 v5, 0, v3
	v_rcp_iflag_f32_e32 v0, v0
	global_atomic_add v4, v219, v223, s[8:9] offset:1024 sc0
	s_add_u32 s8, s8, 0x13a40000
	s_addc_u32 s9, s9, 0
	v_mul_f32_e32 v0, 0x4f7ffffe, v0
	v_cvt_u32_f32_e32 v0, v0
	v_mul_lo_u32 v5, v5, v0
	v_mul_hi_u32 v5, v0, v5
	v_add_u32_e32 v0, v0, v5
	s_waitcnt vmcnt(0)
	v_mul_hi_u32 v0, v4, v0
	v_mul_lo_u32 v5, v0, v3
	v_sub_u32_e32 v5, v4, v5
	v_add_u32_e32 v6, 1, v0
	v_cmp_ge_u32_e32 vcc, v5, v3
	v_add_u32_e32 v4, 1, v4
	s_nop 0
	v_cndmask_b32_e32 v0, v0, v6, vcc
	v_sub_u32_e32 v6, v5, v3
	v_cndmask_b32_e32 v5, v5, v6, vcc
	v_add_u32_e32 v6, 1, v0
	v_cmp_ge_u32_e32 vcc, v5, v3
	s_nop 1
	v_cndmask_b32_e32 v0, v0, v6, vcc
	v_mul_lo_u32 v5, v3, v0
	v_add_u32_e32 v3, v5, v3
	v_cmp_ne_u32_e32 vcc, v4, v3
	s_and_saveexec_b64 s[10:11], vcc
	s_xor_b64 s[10:11], exec, s[10:11]
	s_cbranch_execz .LBB0_814
	v_readlane_b32 s20, v255, 59
	s_mov_b32 s21, 0x36650e
	s_lshr_b32 s21, s21, s26
	s_and_b32 s20, s20, s21
	s_bitcmp1_b32 s20, 0
	s_cbranch_scc1 .Lbar_local_early
	v_add_u32_e32 v6, 1, v5
	v_cmp_eq_u32_e32 vcc, v4, v6
	s_cbranch_vccz .Lbar_early_done
	buffer_wbl2 sc1
	s_branch .Lbar_early_done

; __device__ __forceinline__ unsigned xb_ld(unsigned* p)              { return __hip_atomic_load(p, __ATOMIC_RELAXED, __HIP_MEMORY_SCOPE_AGENT); }
; #define XB_SPIN(cond, bar) do { unsigned _sp = 0; while (cond) { __builtin_amdgcn_s_sleep(1); \
;     if ((++_sp & 255u) == 0u) { if (xb_ld(&(bar)[XB_TMO])) break; if (_sp > XB_SPIN_CAP) { atomicAdd(&(bar)[XB_TMO], 1u); break; } } } } while (0)
; __device__ __forceinline__ void xcd_barrier(const XcdBarrier& b) {
;     ...
;             XB_SPIN(xb_ld(&bar[XB_XGEN(b.x)]) == gen, bar);
;             __builtin_amdgcn_fence(__ATOMIC_ACQUIRE, "agent");
.Lbar_early_done:
	s_waitcnt lgkmcnt(0)
	global_load_dword v2, v227, s[8:9] offset:1024 sc1
	s_add_u32 s22, s8, 0x2400
	s_addc_u32 s23, s9, 0
	s_waitcnt vmcnt(0)
	v_cmp_eq_u32_e32 vcc, v2, v0
	s_and_saveexec_b64 s[18:19], vcc
	s_cbranch_execz .LBB0_813
	s_add_u32 s20, s2, 0x13a40200
	s_addc_u32 s21, s3, 0
	s_mov_b32 s38, 1
	s_mov_b64 s[24:25], 0
	s_branch .LBB0_804

; __device__ __forceinline__ unsigned xb_ld(unsigned* p)              { return __hip_atomic_load(p, __ATOMIC_RELAXED, __HIP_MEMORY_SCOPE_AGENT); }
; __device__ __forceinline__ unsigned xb_add(unsigned* p, unsigned v) { return __hip_atomic_fetch_add(p, v, __ATOMIC_RELAXED, __HIP_MEMORY_SCOPE_AGENT); }
; #define XB_SPIN(cond, bar) do { unsigned _sp = 0; while (cond) { __builtin_amdgcn_s_sleep(1); \
;     if ((++_sp & 255u) == 0u) { if (xb_ld(&(bar)[XB_TMO])) break; if (_sp > XB_SPIN_CAP) { atomicAdd(&(bar)[XB_TMO], 1u); break; } } } } while (0)
; __device__ __forceinline__ void xcd_barrier(const XcdBarrier& b) {
;     ...
;         if (old + 1u == (gen + 1u) * nloc) {
;             __builtin_amdgcn_fence(__ATOMIC_RELEASE, "agent");
;             asm volatile("s_waitcnt vmcnt(0)" ::: "memory");
;             const unsigned og = xb_add(&bar[XB_TOP], 1u);
;             const unsigned tg = og / nx;
;             if (og + 1u == (tg + 1u) * nx) xb_add(&bar[XB_TOPGEN], 1u);
;             else XB_SPIN(xb_ld(&bar[XB_TOPGEN]) == tg, bar);
;             __builtin_amdgcn_fence(__ATOMIC_ACQUIRE, "agent");
;             xb_add(&bar[XB_XGEN(b.x)], 1u);
;             asm volatile("s_waitcnt vmcnt(0)" ::: "memory");
;         } else {
;             XB_SPIN(xb_ld(&bar[XB_XGEN(b.x)]) == gen, bar);
;             __builtin_amdgcn_fence(__ATOMIC_ACQUIRE, "agent");
;             asm volatile("s_waitcnt vmcnt(0)" ::: "memory");
.LBB0_813:
	s_or_b64 exec, exec, s[18:19]
	v_readlane_b32 s18, v255, 59
	s_mov_b32 s19, 0x36650e
	s_lshr_b32 s19, s19, s26
	s_and_b32 s18, s18, s19
	s_bitcmp1_b32 s18, 0
	s_waitcnt vmcnt(0)
	s_cbranch_scc1 .Lbar_noinv
	buffer_inv sc1
	s_waitcnt vmcnt(0)
.Lbar_noinv:
.LBB0_814:
	s_andn2_saveexec_b64 s[10:11], s[10:11]
	s_cbranch_execz .LBB0_832
	s_mov_b64 s[10:11], exec
	v_readlane_b32 s18, v255, 59
	s_mov_b32 s19, 0x36650e
	s_lshr_b32 s19, s19, s26
	s_and_b32 s18, s18, s19
	s_bitcmp1_b32 s18, 0
	s_cbranch_scc1 .LBB0_831
	buffer_wbl2 sc1
	s_waitcnt lgkmcnt(0)
	s_waitcnt vmcnt(0)
	v_mbcnt_lo_u32_b32 v0, s10, 0
	v_mbcnt_hi_u32_b32 v0, s11, v0
	v_cmp_eq_u32_e32 vcc, 0, v0
	s_and_saveexec_b64 s[18:19], vcc
	s_cbranch_execz .LBB0_817
	s_bcnt1_i32_b64 s10, s[10:11]
	v_mov_b32_e32 v3, s10
	v_mov_b32_e32 v4, 0x13a43000
	global_atomic_add v3, v4, v3, s[2:3] offset:1024 sc0
